# candA + grid barrier: XCD leader publishes the generation word before its own L1 invalidate
# speedup vs baseline: 1.0053x; 1.0053x over previous
.LBB0_325:
	s_or_b64 exec, exec, s[6:7]
	v_mov_b32_e32 v1, 0x2000
	v_mov_b32_e32 v2, 1
	s_waitcnt vmcnt(0)
	global_atomic_add v1, v2, s[4:5] offset:1024
	buffer_inv sc1
	s_waitcnt vmcnt(0)

.LBB0_386:
	s_or_b64 exec, exec, s[4:5]
	v_mov_b32_e32 v1, 0x2000
	v_mov_b32_e32 v2, 1
	s_waitcnt vmcnt(0)
	global_atomic_add v1, v2, s[2:3] offset:1024
	buffer_inv sc1
	s_waitcnt vmcnt(0)

.LBB0_389:
	s_or_b64 exec, exec, s[6:7]
	v_readlane_b32 s2, v248, 18
	v_readlane_b32 s3, v248, 19
	s_waitcnt vmcnt(0)
	s_nop 3
	global_atomic_add v3, v202, s[2:3]
	buffer_inv sc1
	s_waitcnt vmcnt(0)

.LBB0_1208:
	s_or_b64 exec, exec, s[8:9]
	v_readlane_b32 s2, v248, 18
	v_readlane_b32 s3, v248, 19
	s_waitcnt vmcnt(0)
	s_nop 3
	global_atomic_add v3, v202, s[2:3]
	buffer_inv sc1
	s_waitcnt vmcnt(0)
